# hot MFMA K-loop / attention loop heads aligned to 64 bytes (.p2align 6, byte-phase pin per docs 9.3)
# baseline (speedup 1.0000x reference)
; DI int get_tid() { int t = threadIdx.x; asm volatile("" : "+v"(t)); return t; }
; DI float zero_f() { float z = 0.f; asm volatile("" : "+v"(z)); return z; }
; template <int BM, class Epi>
; DI void gemm_dma(const u16* __restrict__ X, long ldx, const u16* __restrict__ W, long ldw, int K, char* smem,
;                  int m0, int n0, const Epi& epi) {
;     ...
;   const int tid = get_tid(), lane = tid & 63, wave = tid >> 6;
;   const int lr = lane & 15, g = lane >> 4;
;   const int rd = lr * 64 + ((g ^ ((4 - (lr >> 2)) & 3)) << 4);
;   const int xrow0 = BIG ? wave * 64 : (wave & 1) * (BM / 2);
;   const int wrow0 = BIG ? 0 : (wave >> 1) * 64;
;   f32x4 acc[NT][MT];
;   { const float z = zero_f();
; #pragma unroll
;   for (int a = 0; a < NT; ++a)
; #pragma unroll
;     for (int b = 0; b < MT; ++b) acc[a][b] = (f32x4){z, z, z, z}; }
;   const int wu = __builtin_amdgcn_readfirstlane(wave);
;   const unsigned sbase = (unsigned)__builtin_amdgcn_readfirstlane((int)(unsigned)(size_t)smem);
;   const int r16 = lane >> 2, chunk = (lane & 3) ^ ((4 - (r16 >> 2)) & 3);
;   const u16* xs = X + (long)(wu * XD * 16 + r16) * ldx + (chunk << 3);
;   const u16* ws = W + (long)(wu * 32 + r16) * ldw + (chunk << 3);
;   const long ldx16 = 16 * ldx, ldw16 = 16 * ldw;
;   const unsigned xdst = sbase + wu * XD * 1024, wdst = sbase + BM * 64 + wu * 2048;
;     ...
;   const int nk = K >> 5;
;   __syncthreads();
; #pragma unroll
;   for (int s = 0; s < D - 1; ++s) GD_ISSUE(s)
;   int cur = 0, nxt = D - 1, kt = 0;
.LBB0_30:
	s_and_b64 vcc, exec, s[38:39]
	s_cbranch_vccz .LBB0_25
	s_ashr_i32 s38, s6, 3
	s_ashr_i32 s39, s38, 31
	v_mov_b32_e32 v1, v185
	s_and_b32 s7, s6, 7
	s_lshl_b64 s[40:41], s[38:39], 19
	v_readlane_b32 s8, v252, 24
	v_readlane_b32 s9, v252, 25
	v_lshrrev_b32_e32 v2, 2, v1
	s_add_u32 s8, s8, s40
	s_waitcnt vmcnt(9)
	v_and_b32_e32 v133, 15, v1
	v_bfe_u32 v132, v1, 4, 2
	v_sub_u32_e32 v2, 0, v2
	s_addc_u32 s9, s9, s41
	s_lshl_b32 s10, s7, 18
	v_readlane_b32 s12, v252, 26
	v_lshlrev_b32_e32 v0, 6, v133
	v_bitop3_b32 v2, v132, v2, 3 bitop3:0x78
	v_readlane_b32 s13, v252, 27
	s_add_u32 s12, s12, s10
	v_lshl_or_b32 v134, v2, 4, v0
	v_readfirstlane_b32 s14, v1
	v_lshrrev_b32_e32 v2, 4, v1
	s_addc_u32 s13, s13, 0
	s_ashr_i32 s15, s14, 6
	v_bfe_u32 v6, v1, 2, 4
	v_sub_u32_e32 v14, 0, v2
	s_andn2_b32 s14, s14, 63
	v_xor_b32_e32 v7, v1, v14
	v_or_b32_e32 v2, s14, v6
	v_ashrrev_i32_e32 v3, 31, v2
	v_lshlrev_b32_e32 v7, 4, v7
	v_lshl_or_b32 v6, s15, 5, v6
	v_lshlrev_b64 v[2:3], 11, v[2:3]
	v_and_b32_e32 v182, 48, v7
	v_ashrrev_i32_e32 v7, 31, v6
	v_mov_b32_e32 v0, v183
	v_lshl_add_u64 v[4:5], s[8:9], 0, v[2:3]
	v_lshlrev_b64 v[6:7], 11, v[6:7]
	v_lshl_add_u64 v[4:5], v[4:5], 0, v[182:183]
	v_lshl_add_u64 v[8:9], s[12:13], 0, v[6:7]
	s_lshl_b32 s8, s15, 12
	s_barrier
	s_mov_b32 m0, s8
	s_nop 0
	global_load_lds_dwordx4 v[4:5], off
	s_mov_b64 s[16:17], 0x8000
	v_lshl_add_u64 v[10:11], v[4:5], 0, s[16:17]
	s_or_b32 s13, s8, 0x400
	s_mov_b32 m0, s13
	s_nop 0
	global_load_lds_dwordx4 v[10:11], off
	s_mov_b64 s[18:19], 0x10000
	v_lshl_add_u64 v[10:11], v[4:5], 0, s[18:19]
	s_or_b32 s13, s8, 0x800
	s_mov_b32 m0, s13
	s_nop 0
	global_load_lds_dwordx4 v[10:11], off
	s_mov_b64 s[20:21], 0x18000
	s_lshl_b32 s12, s15, 11
	v_lshl_add_u64 v[10:11], v[4:5], 0, s[20:21]
	s_or_b32 s13, s8, 0xc00
	s_mov_b32 m0, s13
	s_nop 0
	global_load_lds_dwordx4 v[10:11], off
	v_lshl_add_u64 v[8:9], v[8:9], 0, v[182:183]
	s_add_i32 s9, s12, 0x4000
	s_mov_b32 m0, s9
	s_nop 0
	global_load_lds_dwordx4 v[8:9], off
	v_lshl_add_u64 v[10:11], v[8:9], 0, s[16:17]
	s_add_i32 s13, s12, 0x4400
	s_mov_b32 m0, s13
	s_nop 0
	global_load_lds_dwordx4 v[10:11], off
	v_lshl_add_u64 v[10:11], v[4:5], 0, 64
	s_add_i32 s13, s8, 0x6000
	s_mov_b32 m0, s13
	s_nop 0
	global_load_lds_dwordx4 v[10:11], off
	s_mov_b64 s[22:23], 0x8040
	v_lshl_add_u64 v[10:11], v[4:5], 0, s[22:23]
	s_add_i32 s13, s8, 0x6400
	s_mov_b32 m0, s13
	s_nop 0
	global_load_lds_dwordx4 v[10:11], off
	s_mov_b64 s[14:15], 0x10040
	v_lshl_add_u64 v[10:11], v[4:5], 0, s[14:15]
	s_add_i32 s13, s8, 0x6800
	s_mov_b32 m0, s13
	s_nop 0
	global_load_lds_dwordx4 v[10:11], off
	s_mov_b64 s[14:15], 0x18040
	v_lshl_add_u64 v[4:5], v[4:5], 0, s[14:15]
	s_add_i32 s13, s8, 0x6c00
	s_mov_b32 m0, s13
	s_nop 0
	global_load_lds_dwordx4 v[4:5], off
	v_lshl_add_u64 v[12:13], v[8:9], 0, 64
	s_add_i32 s13, s12, 0xa000
	s_mov_b32 m0, s13
	s_nop 0
	global_load_lds_dwordx4 v[12:13], off
	v_lshl_add_u64 v[4:5], v[8:9], 0, s[22:23]
	s_add_i32 s12, s12, 0xa400
	s_mov_b32 m0, s12
	s_nop 0
	global_load_lds_dwordx4 v[4:5], off
	v_and_b32_e32 v135, 0xffffffc0, v1
	v_bitop3_b32 v1, v1, 3, v14 bitop3:0x48
	v_lshl_add_u64 v[4:5], s[34:35], 0, v[6:7]
	v_lshlrev_b32_e32 v182, 4, v1
	v_readlane_b32 s12, v254, 59
	v_lshl_add_u64 v[4:5], v[4:5], 0, v[182:183]
	v_readlane_b32 s13, v254, 60
	v_lshl_add_u64 v[2:3], s[40:41], 0, v[2:3]
	v_or_b32_e32 v2, v2, v182
	s_waitcnt vmcnt(8)
	v_lshl_add_u64 v[128:129], s[12:13], 0, v[4:5]
	v_readlane_b32 s12, v254, 61
	v_readlane_b32 s13, v254, 62
	s_mov_b32 s10, 2
	s_mov_b32 s11, 0
	v_lshlrev_b32_e32 v136, 6, v135
	v_lshl_add_u64 v[130:131], s[12:13], 0, v[2:3]
	s_mov_b64 s[40:41], 0
	v_mov_b32_e32 v1, v0
	v_mov_b32_e32 v2, v0
	v_mov_b32_e32 v3, v0
	v_mov_b32_e32 v4, v0
	v_mov_b32_e32 v5, v0
	v_mov_b32_e32 v6, v0
	v_mov_b32_e32 v7, v0
	v_mov_b32_e32 v8, v0
	v_mov_b32_e32 v9, v0
	v_mov_b32_e32 v10, v0
	v_mov_b32_e32 v11, v0
	v_mov_b32_e32 v12, v0
	v_mov_b32_e32 v13, v0
	v_mov_b32_e32 v14, v0
	v_mov_b32_e32 v15, v0
	s_waitcnt vmcnt(7)
	v_mov_b32_e32 v16, v0
	v_mov_b32_e32 v17, v0
	v_mov_b32_e32 v18, v0
	v_mov_b32_e32 v19, v0
	s_waitcnt vmcnt(5)
	v_mov_b32_e32 v20, v0
	v_mov_b32_e32 v21, v0
	v_mov_b32_e32 v22, v0
	v_mov_b32_e32 v23, v0
	v_mov_b32_e32 v24, v0
	v_mov_b32_e32 v25, v0
	v_mov_b32_e32 v26, v0
	v_mov_b32_e32 v27, v0
	s_waitcnt vmcnt(4)
	v_mov_b32_e32 v28, v0
	v_mov_b32_e32 v29, v0
	v_mov_b32_e32 v30, v0
	v_mov_b32_e32 v31, v0
	v_mov_b32_e32 v32, v0
	v_mov_b32_e32 v33, v0
	v_mov_b32_e32 v34, v0
	v_mov_b32_e32 v35, v0
	v_mov_b32_e32 v36, v0
	v_mov_b32_e32 v37, v0
	v_mov_b32_e32 v38, v0
	v_mov_b32_e32 v39, v0
	v_mov_b32_e32 v40, v0
	v_mov_b32_e32 v41, v0
	v_mov_b32_e32 v42, v0
	v_mov_b32_e32 v43, v0
	v_mov_b32_e32 v44, v0
	v_mov_b32_e32 v45, v0
	v_mov_b32_e32 v46, v0
	v_mov_b32_e32 v47, v0
	v_mov_b32_e32 v48, v0
	v_mov_b32_e32 v49, v0
	v_mov_b32_e32 v50, v0
	v_mov_b32_e32 v51, v0
	v_mov_b32_e32 v52, v0
	v_mov_b32_e32 v53, v0
	v_mov_b32_e32 v54, v0
	v_mov_b32_e32 v55, v0
	v_mov_b32_e32 v56, v0
	v_mov_b32_e32 v57, v0
	v_mov_b32_e32 v58, v0
	v_mov_b32_e32 v59, v0
	v_mov_b32_e32 v60, v0
	v_mov_b32_e32 v61, v0
	v_mov_b32_e32 v62, v0
	v_mov_b32_e32 v63, v0
	v_mov_b32_e32 v64, v0
	v_mov_b32_e32 v65, v0
	v_mov_b32_e32 v66, v0
	v_mov_b32_e32 v67, v0
	v_mov_b32_e32 v68, v0
	v_mov_b32_e32 v69, v0
	v_mov_b32_e32 v70, v0
	v_mov_b32_e32 v71, v0
	v_mov_b32_e32 v72, v0
	v_mov_b32_e32 v73, v0
	v_mov_b32_e32 v74, v0
	v_mov_b32_e32 v75, v0
	v_mov_b32_e32 v76, v0
	v_mov_b32_e32 v77, v0
	v_mov_b32_e32 v78, v0
	v_mov_b32_e32 v79, v0
	v_mov_b32_e32 v80, v0
	v_mov_b32_e32 v81, v0
	v_mov_b32_e32 v82, v0
	v_mov_b32_e32 v83, v0
	v_mov_b32_e32 v84, v0
	v_mov_b32_e32 v85, v0
	v_mov_b32_e32 v86, v0
	v_mov_b32_e32 v87, v0
	v_mov_b32_e32 v88, v0
	v_mov_b32_e32 v89, v0
	v_mov_b32_e32 v90, v0
	v_mov_b32_e32 v91, v0
	v_mov_b32_e32 v92, v0
	v_mov_b32_e32 v93, v0
	v_mov_b32_e32 v94, v0
	v_mov_b32_e32 v95, v0
	s_waitcnt vmcnt(0)
	v_mov_b32_e32 v96, v0
	v_mov_b32_e32 v97, v0
	v_mov_b32_e32 v98, v0
	v_mov_b32_e32 v99, v0
	v_mov_b32_e32 v100, v0
	v_mov_b32_e32 v101, v0
	v_mov_b32_e32 v102, v0
	v_mov_b32_e32 v103, v0
	v_mov_b32_e32 v104, v0
	v_mov_b32_e32 v105, v0
	v_mov_b32_e32 v106, v0
	v_mov_b32_e32 v107, v0
	v_mov_b32_e32 v108, v0
	v_mov_b32_e32 v109, v0
	v_mov_b32_e32 v110, v0
	v_mov_b32_e32 v111, v0
	v_mov_b32_e32 v112, v0
	v_mov_b32_e32 v113, v0
	v_mov_b32_e32 v114, v0
	v_mov_b32_e32 v115, v0
	v_mov_b32_e32 v116, v0
	v_mov_b32_e32 v117, v0
	v_mov_b32_e32 v118, v0
	v_mov_b32_e32 v119, v0
	v_mov_b32_e32 v120, v0
	v_mov_b32_e32 v121, v0
	v_mov_b32_e32 v122, v0
	v_mov_b32_e32 v123, v0
	v_mov_b32_e32 v124, v0
	v_mov_b32_e32 v125, v0
	v_mov_b32_e32 v126, v0
	v_mov_b32_e32 v127, v0
	.p2align	6

; DI int get_bid() { int b = blockIdx.x; asm volatile("" : "+s"(b)); return b; }
; DI void phase_odd(const Params& p, int o, int sub, char* smem) {
;     ...
;     for (int t = get_bid(); t < 1088 + 832; t += gridDim.x) {
;       if (t < 1088) {
;         int b, tm, tn; long kv0, ld; u16* C;
;         if (t < 512) { b = t >> 8; const int r = t & 255; tm = r >> 6; tn = r & 63; kv0 = (long)b * 8192; ld = 8192; C = vtb + (size_t)b * 1024 * 8192; }
;         else { const int u = t - 512; b = u / 36; const int r = u % 36; tm = r / 9; tn = r % 9; kv0 = (long)M_PROMPT + (long)b * KSTR_S; ld = KSTR_S;
;                C = vtb + (size_t)2 * 1024 * 8192 + (size_t)b * 1024 * KSTR_S; }
;         EpiVT ev{C, ld};
;         gemm_dma<256>(W + WO_KV + (size_t)(1024 + tm * 256) * 256, 256, ckvb + (size_t)(kv0 + tn * 128) * 256, 256, 256, smem, tm * 256, tn * 128, ev);
;       } else {
;         knope_tile(p, 256 + (t - 1088), smem);
;       }
.LBB0_81:
	s_mov_b32 s4, s2
	s_waitcnt vmcnt(0)
	s_branch .LBB0_84
	.p2align	6

; DI int get_bid() { int b = blockIdx.x; asm volatile("" : "+s"(b)); return b; }
; DI void phase_odd(const Params& p, int o, int sub, char* smem) {
;     ...
;     for (int t = get_bid(); t < 1088 + 832; t += gridDim.x) {
;       if (t < 1088) {
;         int b, tm, tn; long kv0, ld; u16* C;
;         if (t < 512) { b = t >> 8; const int r = t & 255; tm = r >> 6; tn = r & 63; kv0 = (long)b * 8192; ld = 8192; C = vtb + (size_t)b * 1024 * 8192; }
;         else { const int u = t - 512; b = u / 36; const int r = u % 36; tm = r / 9; tn = r % 9; kv0 = (long)M_PROMPT + (long)b * KSTR_S; ld = KSTR_S;
;                C = vtb + (size_t)2 * 1024 * 8192 + (size_t)b * 1024 * KSTR_S; }
;         EpiVT ev{C, ld};
;         gemm_dma<256>(W + WO_KV + (size_t)(1024 + tm * 256) * 256, 256, ckvb + (size_t)(kv0 + tn * 128) * 256, 256, 256, smem, tm * 256, tn * 128, ev);
;       } else {
;         knope_tile(p, 256 + (t - 1088), smem);
;       }
.LBB0_83:
	v_readlane_b32 s8, v255, 5
	v_readlane_b32 s14, v255, 11
	v_readlane_b32 s9, v255, 6
	v_readlane_b32 s10, v255, 7
	v_readlane_b32 s11, v255, 8
	v_readlane_b32 s12, v255, 9
	v_readlane_b32 s13, v255, 10
	v_readlane_b32 s15, v255, 12
	s_add_i32 s4, s4, s14
	.p2align	6

; DI int get_bid() { int b = blockIdx.x; asm volatile("" : "+s"(b)); return b; }
; DI void phase_odd(const Params& p, int o, int sub, char* smem) {
;     ...
;     for (int t = get_bid(); t < 1584 + 256; t += gridDim.x) {
;       if (t < 1584) {
;         const int tm = t / 12, tn = t % 12;
;         const int t2 = t + gridDim.x, tm2 = t2 / 12, tn2 = t2 % 12;
;         const bool nx = t2 < 1584;
.LBB0_98:
	s_load_dword s5, s[72:73], 0x10
	s_waitcnt lgkmcnt(0)
	s_lshr_b32 s5, s5, 16
	s_cmp_lg_u32 s5, 0
	s_cselect_b64 s[6:7], -1, 0
	s_cmp_lg_u64 s[6:7], 0
	s_addc_u32 s5, s4, 0
	s_cmpk_gt_i32 s5, 0x72f
	s_cbranch_scc1 .LBB0_114
	.p2align	6

; DI int get_tid() { int t = threadIdx.x; asm volatile("" : "+v"(t)); return t; }
; DI float zero_f() { float z = 0.f; asm volatile("" : "+v"(z)); return z; }
; template <int MT, class Epi>
; DI void gemm_tile(const u16* __restrict__ X, long ldx, const u16* __restrict__ W, long ldw, int K, char* smem,
;                   int m0, int n0, const Epi& epi, bool pre = false, const u16* Xn = nullptr, const u16* Wn = nullptr) {
;   const int tid = get_tid(), lane = tid & 63, wave = tid >> 6;
;   const int wm = wave & 1, wn = wave >> 1;
;   const int lr = lane & 15, g = lane >> 4;
;   const int rsw = (lr >> 1) & 7;
;   f32x4 acc[4][MT];
;   { const float z = zero_f();
; #pragma unroll
;   for (int a = 0; a < 4; ++a)
; #pragma unroll
;     for (int b = 0; b < MT; ++b) acc[a][b] = (f32x4){z, z, z, z}; }
;   const int wu = __builtin_amdgcn_readfirstlane(wave);
;   const unsigned sbase = (unsigned)__builtin_amdgcn_readfirstlane((int)(unsigned)(size_t)smem);
;   const int r8 = lane >> 3, c0 = (lane & 7) ^ (r8 >> 1);
;   const long oxe = (long)(wu * MT * 8 + r8) * ldx + (c0 << 3), oxo = (long)(wu * MT * 8 + r8) * ldx + ((c0 ^ 4) << 3);
;   const long owe = (long)(wu * 32 + r8) * ldw + (c0 << 3), owo = (long)(wu * 32 + r8) * ldw + ((c0 ^ 4) << 3);
;   const u16 *xe = X + oxe, *xo = X + oxo, *we = W + owe, *wo = W + owo;
;   const long ldx8 = 8 * ldx, ldw8 = 8 * ldw;
;   const unsigned xdst = sbase + wu * MT * 1024, wdst = sbase + 16384 + wu * 4096;
;     ...
;   if (!pre) {
;     __syncthreads();
;     GT_DMA(0u)
;   } else {
;     xe += 64; xo += 64; we += 64; wo += 64;
;   }
;   const int nk = K >> 6;
;   int kt = 0;
.LBB0_143:
	v_and_b32_e32 v78, 1, v6
	v_and_b32_e32 v79, 15, v5
	v_lshrrev_b32_e32 v6, 1, v5
	v_ashrrev_i32_e32 v80, 7, v5
	v_bfe_u32 v5, v5, 1, 3
	v_bitop3_b32 v5, v1, v5, 4 bitop3:0x36
	v_add_u32_e32 v4, s7, v4
	v_lshlrev_b32_e32 v83, 4, v5
	v_ashrrev_i32_e32 v5, 31, v4
	v_xor_b32_e32 v8, 32, v7
	v_bitop3_b32 v6, v1, v6, 7 bitop3:0x78
	v_lshlrev_b64 v[4:5], 11, v[4:5]
	v_lshlrev_b32_e32 v85, 4, v6
	v_lshl_add_u64 v[6:7], s[44:45], 0, v[4:5]
	v_lshlrev_b32_e32 v182, 1, v8
	v_readlane_b32 s8, v255, 5
	v_lshl_add_u64 v[8:9], v[6:7], 0, v[182:183]
	v_readlane_b32 s12, v255, 9
	v_readlane_b32 s13, v255, 10
	v_lshl_add_u64 v[4:5], s[40:41], 0, v[4:5]
	v_lshlrev_b32_e32 v81, 13, v78
	v_lshl_add_u64 v[70:71], s[12:13], 0, v[8:9]
	v_lshlrev_b32_e32 v8, 4, v3
	v_mov_b32_e32 v9, v183
	v_lshl_add_u64 v[6:7], v[6:7], 0, v[8:9]
	v_lshl_add_u64 v[72:73], s[12:13], 0, v[6:7]
	v_lshl_add_u64 v[6:7], v[4:5], 0, v[182:183]
	v_lshl_add_u64 v[4:5], v[4:5], 0, v[8:9]
	v_lshlrev_b32_e32 v82, 7, v79
	v_lshlrev_b32_e32 v84, 13, v80
	v_lshl_add_u64 v[74:75], s[0:1], 0, v[6:7]
	v_lshl_add_u64 v[76:77], s[12:13], 0, v[4:5]
	s_mov_b64 s[40:41], 0
	s_mov_b32 s8, 0
	v_mov_b32_e32 v3, v2
	v_mov_b32_e32 v4, v2
	v_mov_b32_e32 v5, v2
	v_mov_b32_e32 v6, v2
	v_mov_b32_e32 v7, v2
	v_mov_b32_e32 v8, v2
	v_mov_b32_e32 v9, v2
	v_mov_b32_e32 v10, v2
	v_mov_b32_e32 v11, v2
	v_mov_b32_e32 v12, v2
	v_mov_b32_e32 v13, v2
	v_mov_b32_e32 v14, v2
	v_mov_b32_e32 v15, v2
	v_mov_b32_e32 v16, v2
	v_mov_b32_e32 v17, v2
	v_mov_b32_e32 v18, v2
	v_mov_b32_e32 v19, v2
	v_mov_b32_e32 v20, v2
	v_mov_b32_e32 v21, v2
	v_mov_b32_e32 v22, v2
	v_mov_b32_e32 v23, v2
	v_mov_b32_e32 v24, v2
	v_mov_b32_e32 v25, v2
	v_mov_b32_e32 v26, v2
	v_mov_b32_e32 v27, v2
	v_mov_b32_e32 v28, v2
	v_mov_b32_e32 v29, v2
	v_mov_b32_e32 v30, v2
	v_mov_b32_e32 v31, v2
	v_mov_b32_e32 v32, v2
	v_mov_b32_e32 v33, v2
	v_mov_b32_e32 v34, v2
	v_mov_b32_e32 v35, v2
	v_mov_b32_e32 v36, v2
	v_mov_b32_e32 v37, v2
	v_mov_b32_e32 v38, v2
	v_mov_b32_e32 v39, v2
	v_mov_b32_e32 v40, v2
	v_mov_b32_e32 v41, v2
	v_mov_b32_e32 v42, v2
	v_mov_b32_e32 v43, v2
	v_mov_b32_e32 v44, v2
	v_mov_b32_e32 v45, v2
	v_mov_b32_e32 v46, v2
	v_mov_b32_e32 v47, v2
	v_mov_b32_e32 v48, v2
	v_mov_b32_e32 v49, v2
	v_mov_b32_e32 v50, v2
	v_mov_b32_e32 v51, v2
	v_mov_b32_e32 v52, v2
	v_mov_b32_e32 v53, v2
	v_mov_b32_e32 v54, v2
	v_mov_b32_e32 v55, v2
	v_mov_b32_e32 v56, v2
	v_mov_b32_e32 v57, v2
	v_mov_b32_e32 v58, v2
	v_mov_b32_e32 v59, v2
	v_mov_b32_e32 v60, v2
	v_mov_b32_e32 v61, v2
	v_mov_b32_e32 v62, v2
	v_mov_b32_e32 v63, v2
	v_mov_b32_e32 v64, v2
	v_mov_b32_e32 v65, v2
	v_readlane_b32 s9, v255, 6
	v_readlane_b32 s10, v255, 7
	v_readlane_b32 s11, v255, 8
	v_readlane_b32 s14, v255, 11
	v_readlane_b32 s15, v255, 12
	.p2align	6

; DI int get_tid() { int t = threadIdx.x; asm volatile("" : "+v"(t)); return t; }
; DI float zero_f() { float z = 0.f; asm volatile("" : "+v"(z)); return z; }
; template <int BM, class Epi>
; DI void gemm_dma(const u16* __restrict__ X, long ldx, const u16* __restrict__ W, long ldw, int K, char* smem,
;                  int m0, int n0, const Epi& epi) {
;     ...
;   const int tid = get_tid(), lane = tid & 63, wave = tid >> 6;
;   const int lr = lane & 15, g = lane >> 4;
;   const int rd = lr * 64 + ((g ^ ((4 - (lr >> 2)) & 3)) << 4);
;   const int xrow0 = BIG ? wave * 64 : (wave & 1) * (BM / 2);
;   const int wrow0 = BIG ? 0 : (wave >> 1) * 64;
;   f32x4 acc[NT][MT];
;   { const float z = zero_f();
; #pragma unroll
;   for (int a = 0; a < NT; ++a)
; #pragma unroll
;     for (int b = 0; b < MT; ++b) acc[a][b] = (f32x4){z, z, z, z}; }
;   const int wu = __builtin_amdgcn_readfirstlane(wave);
;   const unsigned sbase = (unsigned)__builtin_amdgcn_readfirstlane((int)(unsigned)(size_t)smem);
;   const int r16 = lane >> 2, chunk = (lane & 3) ^ ((4 - (r16 >> 2)) & 3);
;   const u16* xs = X + (long)(wu * XD * 16 + r16) * ldx + (chunk << 3);
;   const u16* ws = W + (long)(wu * 32 + r16) * ldw + (chunk << 3);
;   const long ldx16 = 16 * ldx, ldw16 = 16 * ldw;
;   const unsigned xdst = sbase + wu * XD * 1024, wdst = sbase + BM * 64 + wu * 2048;
;     ...
;   const int nk = K >> 5;
;   __syncthreads();
; #pragma unroll
;   for (int s = 0; s < D - 1; ++s) GD_ISSUE(s)
;   int cur = 0, nxt = D - 1, kt = 0;
.LBB0_290:
	s_and_b64 vcc, exec, s[38:39]
	s_cbranch_vccz .LBB0_285
	s_ashr_i32 s38, s6, 3
	s_ashr_i32 s39, s38, 31
	v_mov_b32_e32 v3, v185
	s_and_b32 s7, s6, 7
	s_lshl_b64 s[40:41], s[38:39], 20
	v_readlane_b32 s8, v252, 35
	v_readlane_b32 s9, v252, 36
	v_lshrrev_b32_e32 v4, 2, v3
	s_add_u32 s8, s8, s40
	v_and_b32_e32 v134, 15, v3
	v_bfe_u32 v1, v3, 4, 2
	v_sub_u32_e32 v4, 0, v4
	s_addc_u32 s9, s9, s41
	s_lshl_b32 s10, s7, 19
	v_readlane_b32 s12, v252, 39
	v_lshlrev_b32_e32 v2, 6, v134
	v_bitop3_b32 v4, v1, v4, 3 bitop3:0x78
	v_readlane_b32 s13, v252, 40
	s_add_u32 s12, s12, s10
	v_lshl_or_b32 v135, v4, 4, v2
	v_readfirstlane_b32 s14, v3
	v_lshrrev_b32_e32 v4, 4, v3
	s_addc_u32 s13, s13, 0
	s_ashr_i32 s15, s14, 6
	v_bfe_u32 v8, v3, 2, 4
	v_sub_u32_e32 v16, 0, v4
	s_andn2_b32 s14, s14, 63
	v_xor_b32_e32 v9, v3, v16
	v_or_b32_e32 v4, s14, v8
	v_ashrrev_i32_e32 v5, 31, v4
	v_lshlrev_b32_e32 v9, 4, v9
	v_lshl_or_b32 v8, s15, 5, v8
	v_lshlrev_b64 v[4:5], 12, v[4:5]
	v_and_b32_e32 v182, 48, v9
	v_ashrrev_i32_e32 v9, 31, v8
	v_mov_b32_e32 v2, v183
	v_lshl_add_u64 v[6:7], s[8:9], 0, v[4:5]
	v_lshlrev_b64 v[8:9], 12, v[8:9]
	v_lshl_add_u64 v[6:7], v[6:7], 0, v[182:183]
	v_lshl_add_u64 v[10:11], s[12:13], 0, v[8:9]
	s_lshl_b32 s8, s15, 12
	s_barrier
	s_mov_b32 m0, s8
	s_nop 0
	global_load_lds_dwordx4 v[6:7], off
	s_mov_b64 s[16:17], 0x10000
	v_lshl_add_u64 v[12:13], v[6:7], 0, s[16:17]
	s_or_b32 s13, s8, 0x400
	s_mov_b32 m0, s13
	s_nop 0
	global_load_lds_dwordx4 v[12:13], off
	s_mov_b64 s[20:21], 0x20000
	v_lshl_add_u64 v[12:13], v[6:7], 0, s[20:21]
	s_or_b32 s13, s8, 0x800
	s_mov_b32 m0, s13
	s_nop 0
	global_load_lds_dwordx4 v[12:13], off
	s_mov_b64 s[22:23], 0x30000
	s_lshl_b32 s12, s15, 11
	v_lshl_add_u64 v[12:13], v[6:7], 0, s[22:23]
	s_or_b32 s13, s8, 0xc00
	s_mov_b32 m0, s13
	s_nop 0
	global_load_lds_dwordx4 v[12:13], off
	v_lshl_add_u64 v[10:11], v[10:11], 0, v[182:183]
	s_add_i32 s9, s12, 0x4000
	s_mov_b32 m0, s9
	s_nop 0
	global_load_lds_dwordx4 v[10:11], off
	v_lshl_add_u64 v[12:13], v[10:11], 0, s[16:17]
	s_add_i32 s13, s12, 0x4400
	s_mov_b32 m0, s13
	s_nop 0
	global_load_lds_dwordx4 v[12:13], off
	v_lshl_add_u64 v[12:13], v[6:7], 0, 64
	s_add_i32 s13, s8, 0x6000
	s_mov_b32 m0, s13
	s_nop 0
	global_load_lds_dwordx4 v[12:13], off
	s_mov_b64 s[18:19], 0x10040
	v_lshl_add_u64 v[12:13], v[6:7], 0, s[18:19]
	s_add_i32 s13, s8, 0x6400
	s_mov_b32 m0, s13
	s_nop 0
	global_load_lds_dwordx4 v[12:13], off
	s_mov_b64 s[14:15], 0x20040
	v_lshl_add_u64 v[12:13], v[6:7], 0, s[14:15]
	s_add_i32 s13, s8, 0x6800
	s_mov_b32 m0, s13
	s_nop 0
	global_load_lds_dwordx4 v[12:13], off
	s_mov_b64 s[14:15], 0x30040
	v_lshl_add_u64 v[6:7], v[6:7], 0, s[14:15]
	s_add_i32 s13, s8, 0x6c00
	s_mov_b32 m0, s13
	s_nop 0
	global_load_lds_dwordx4 v[6:7], off
	v_lshl_add_u64 v[14:15], v[10:11], 0, 64
	s_add_i32 s13, s12, 0xa000
	s_mov_b32 m0, s13
	s_nop 0
	global_load_lds_dwordx4 v[14:15], off
	v_lshl_add_u64 v[6:7], v[10:11], 0, s[18:19]
	s_add_i32 s12, s12, 0xa400
	s_mov_b32 m0, s12
	s_nop 0
	global_load_lds_dwordx4 v[6:7], off
	v_and_b32_e32 v136, 0xffffffc0, v3
	v_bitop3_b32 v3, v3, 3, v16 bitop3:0x48
	v_lshl_add_u64 v[6:7], s[34:35], 0, v[8:9]
	v_lshlrev_b32_e32 v182, 4, v3
	v_readlane_b32 s12, v255, 3
	v_lshl_add_u64 v[6:7], v[6:7], 0, v[182:183]
	v_readlane_b32 s13, v255, 4
	v_lshl_add_u64 v[4:5], s[40:41], 0, v[4:5]
	v_or_b32_e32 v4, v4, v182
	v_lshl_add_u64 v[130:131], s[12:13], 0, v[6:7]
	v_readlane_b32 s12, v255, 13
	v_readlane_b32 s13, v255, 14
	s_mov_b32 s10, 2
	s_mov_b32 s11, 0
	v_lshlrev_b32_e32 v137, 6, v136
	v_lshl_add_u64 v[132:133], s[12:13], 0, v[4:5]
	s_mov_b64 s[40:41], 0
	v_mov_b32_e32 v3, v2
	v_mov_b32_e32 v4, v2
	v_mov_b32_e32 v5, v2
	v_mov_b32_e32 v6, v2
	v_mov_b32_e32 v7, v2
	v_mov_b32_e32 v8, v2
	v_mov_b32_e32 v9, v2
	v_mov_b32_e32 v10, v2
	v_mov_b32_e32 v11, v2
	v_mov_b32_e32 v12, v2
	v_mov_b32_e32 v13, v2
	v_mov_b32_e32 v14, v2
	v_mov_b32_e32 v15, v2
	v_mov_b32_e32 v16, v2
	v_mov_b32_e32 v17, v2
	v_mov_b32_e32 v18, v2
	v_mov_b32_e32 v19, v2
	v_mov_b32_e32 v20, v2
	v_mov_b32_e32 v21, v2
	v_mov_b32_e32 v22, v2
	v_mov_b32_e32 v23, v2
	v_mov_b32_e32 v24, v2
	v_mov_b32_e32 v25, v2
	v_mov_b32_e32 v26, v2
	v_mov_b32_e32 v27, v2
	v_mov_b32_e32 v28, v2
	v_mov_b32_e32 v29, v2
	v_mov_b32_e32 v30, v2
	v_mov_b32_e32 v31, v2
	v_mov_b32_e32 v32, v2
	v_mov_b32_e32 v33, v2
	v_mov_b32_e32 v34, v2
	v_mov_b32_e32 v35, v2
	v_mov_b32_e32 v36, v2
	v_mov_b32_e32 v37, v2
	v_mov_b32_e32 v38, v2
	v_mov_b32_e32 v39, v2
	v_mov_b32_e32 v40, v2
	v_mov_b32_e32 v41, v2
	v_mov_b32_e32 v42, v2
	v_mov_b32_e32 v43, v2
	v_mov_b32_e32 v44, v2
	v_mov_b32_e32 v45, v2
	v_mov_b32_e32 v46, v2
	v_mov_b32_e32 v47, v2
	v_mov_b32_e32 v48, v2
	v_mov_b32_e32 v49, v2
	v_mov_b32_e32 v50, v2
	v_mov_b32_e32 v51, v2
	v_mov_b32_e32 v52, v2
	v_mov_b32_e32 v53, v2
	v_mov_b32_e32 v54, v2
	v_mov_b32_e32 v55, v2
	v_mov_b32_e32 v56, v2
	v_mov_b32_e32 v57, v2
	v_mov_b32_e32 v58, v2
	v_mov_b32_e32 v59, v2
	v_mov_b32_e32 v60, v2
	v_mov_b32_e32 v61, v2
	v_mov_b32_e32 v62, v2
	v_mov_b32_e32 v63, v2
	v_mov_b32_e32 v64, v2
	v_mov_b32_e32 v65, v2
	v_mov_b32_e32 v66, v2
	v_mov_b32_e32 v67, v2
	v_mov_b32_e32 v68, v2
	v_mov_b32_e32 v69, v2
	v_mov_b32_e32 v70, v2
	v_mov_b32_e32 v71, v2
	v_mov_b32_e32 v72, v2
	v_mov_b32_e32 v73, v2
	v_mov_b32_e32 v74, v2
	v_mov_b32_e32 v75, v2
	v_mov_b32_e32 v76, v2
	v_mov_b32_e32 v77, v2
	v_mov_b32_e32 v78, v2
	v_mov_b32_e32 v79, v2
	v_mov_b32_e32 v80, v2
	v_mov_b32_e32 v81, v2
	v_mov_b32_e32 v82, v2
	v_mov_b32_e32 v83, v2
	v_mov_b32_e32 v84, v2
	v_mov_b32_e32 v85, v2
	v_mov_b32_e32 v86, v2
	v_mov_b32_e32 v87, v2
	v_mov_b32_e32 v88, v2
	v_mov_b32_e32 v89, v2
	v_mov_b32_e32 v90, v2
	v_mov_b32_e32 v91, v2
	v_mov_b32_e32 v92, v2
	v_mov_b32_e32 v93, v2
	v_mov_b32_e32 v94, v2
	v_mov_b32_e32 v95, v2
	v_mov_b32_e32 v96, v2
	v_mov_b32_e32 v97, v2
	v_mov_b32_e32 v98, v2
	v_mov_b32_e32 v99, v2
	v_mov_b32_e32 v100, v2
	v_mov_b32_e32 v101, v2
	v_mov_b32_e32 v102, v2
	v_mov_b32_e32 v103, v2
	v_mov_b32_e32 v104, v2
	v_mov_b32_e32 v105, v2
	v_mov_b32_e32 v106, v2
	v_mov_b32_e32 v107, v2
	v_mov_b32_e32 v108, v2
	v_mov_b32_e32 v109, v2
	v_mov_b32_e32 v110, v2
	v_mov_b32_e32 v111, v2
	v_mov_b32_e32 v112, v2
	v_mov_b32_e32 v113, v2
	v_mov_b32_e32 v114, v2
	v_mov_b32_e32 v115, v2
	v_mov_b32_e32 v116, v2
	v_mov_b32_e32 v117, v2
	v_mov_b32_e32 v118, v2
	v_mov_b32_e32 v119, v2
	v_mov_b32_e32 v120, v2
	v_mov_b32_e32 v121, v2
	v_mov_b32_e32 v122, v2
	v_mov_b32_e32 v123, v2
	v_mov_b32_e32 v124, v2
	v_mov_b32_e32 v125, v2
	v_mov_b32_e32 v126, v2
	v_mov_b32_e32 v127, v2
	v_mov_b32_e32 v128, v2
	v_mov_b32_e32 v129, v2
	.p2align	6

; DI int get_tid() { int t = threadIdx.x; asm volatile("" : "+v"(t)); return t; }
; DI float zero_f() { float z = 0.f; asm volatile("" : "+v"(z)); return z; }
; template <int MT, class Epi>
; DI void gemm_tile(const u16* __restrict__ X, long ldx, const u16* __restrict__ W, long ldw, int K, char* smem,
;                   int m0, int n0, const Epi& epi, bool pre = false, const u16* Xn = nullptr, const u16* Wn = nullptr) {
;   const int tid = get_tid(), lane = tid & 63, wave = tid >> 6;
;   const int wm = wave & 1, wn = wave >> 1;
;   const int lr = lane & 15, g = lane >> 4;
;   const int rsw = (lr >> 1) & 7;
;   f32x4 acc[4][MT];
;   { const float z = zero_f();
; #pragma unroll
;   for (int a = 0; a < 4; ++a)
; #pragma unroll
;     for (int b = 0; b < MT; ++b) acc[a][b] = (f32x4){z, z, z, z}; }
;   const int wu = __builtin_amdgcn_readfirstlane(wave);
;   const unsigned sbase = (unsigned)__builtin_amdgcn_readfirstlane((int)(unsigned)(size_t)smem);
;   const int r8 = lane >> 3, c0 = (lane & 7) ^ (r8 >> 1);
;   const long oxe = (long)(wu * MT * 8 + r8) * ldx + (c0 << 3), oxo = (long)(wu * MT * 8 + r8) * ldx + ((c0 ^ 4) << 3);
;   const long owe = (long)(wu * 32 + r8) * ldw + (c0 << 3), owo = (long)(wu * 32 + r8) * ldw + ((c0 ^ 4) << 3);
;   const u16 *xe = X + oxe, *xo = X + oxo, *we = W + owe, *wo = W + owo;
;   const long ldx8 = 8 * ldx, ldw8 = 8 * ldw;
;   const unsigned xdst = sbase + wu * MT * 1024, wdst = sbase + 16384 + wu * 4096;
;     ...
;   if (!pre) {
;     __syncthreads();
;     GT_DMA(0u)
;   } else {
;     xe += 64; xo += 64; we += 64; wo += 64;
;   }
;   const int nk = K >> 6;
;   int kt = 0;
.LBB0_421:
	v_xor_b32_e32 v8, 32, v6
	v_and_b32_e32 v79, 15, v5
	v_lshrrev_b32_e32 v6, 1, v5
	v_ashrrev_i32_e32 v80, 7, v5
	v_bfe_u32 v5, v5, 1, 3
	v_bitop3_b32 v5, v78, v5, 4 bitop3:0x36
	v_add_u32_e32 v4, s7, v4
	v_lshlrev_b32_e32 v83, 4, v5
	v_ashrrev_i32_e32 v5, 31, v4
	v_bitop3_b32 v6, v78, v6, 7 bitop3:0x78
	v_lshlrev_b64 v[4:5], 11, v[4:5]
	v_lshlrev_b32_e32 v85, 4, v6
	v_lshl_add_u64 v[6:7], s[44:45], 0, v[4:5]
	v_lshlrev_b32_e32 v182, 1, v8
	v_readlane_b32 s8, v255, 5
	v_lshl_add_u64 v[8:9], v[6:7], 0, v[182:183]
	v_readlane_b32 s12, v255, 9
	v_readlane_b32 s13, v255, 10
	v_lshl_add_u64 v[4:5], s[40:41], 0, v[4:5]
	v_and_b32_e32 v1, 1, v1
	v_lshl_add_u64 v[70:71], s[12:13], 0, v[8:9]
	v_lshlrev_b32_e32 v8, 4, v3
	v_mov_b32_e32 v9, v183
	v_lshl_add_u64 v[6:7], v[6:7], 0, v[8:9]
	v_lshl_add_u64 v[72:73], s[12:13], 0, v[6:7]
	v_lshl_add_u64 v[6:7], v[4:5], 0, v[182:183]
	v_lshl_add_u64 v[4:5], v[4:5], 0, v[8:9]
	v_lshlrev_b32_e32 v81, 13, v1
	v_lshlrev_b32_e32 v82, 7, v79
	v_lshlrev_b32_e32 v84, 13, v80
	v_lshl_add_u64 v[74:75], s[0:1], 0, v[6:7]
	v_lshl_add_u64 v[76:77], s[12:13], 0, v[4:5]
	s_mov_b64 s[40:41], 0
	s_mov_b32 s8, 0
	v_mov_b32_e32 v3, v2
	v_mov_b32_e32 v4, v2
	v_mov_b32_e32 v5, v2
	v_mov_b32_e32 v6, v2
	v_mov_b32_e32 v7, v2
	v_mov_b32_e32 v8, v2
	v_mov_b32_e32 v9, v2
	v_mov_b32_e32 v10, v2
	v_mov_b32_e32 v11, v2
	v_mov_b32_e32 v12, v2
	v_mov_b32_e32 v13, v2
	v_mov_b32_e32 v14, v2
	v_mov_b32_e32 v15, v2
	v_mov_b32_e32 v16, v2
	v_mov_b32_e32 v17, v2
	v_mov_b32_e32 v18, v2
	v_mov_b32_e32 v19, v2
	v_mov_b32_e32 v20, v2
	v_mov_b32_e32 v21, v2
	v_mov_b32_e32 v22, v2
	v_mov_b32_e32 v23, v2
	v_mov_b32_e32 v24, v2
	v_mov_b32_e32 v25, v2
	v_mov_b32_e32 v26, v2
	v_mov_b32_e32 v27, v2
	v_mov_b32_e32 v28, v2
	v_mov_b32_e32 v29, v2
	v_mov_b32_e32 v30, v2
	v_mov_b32_e32 v31, v2
	v_mov_b32_e32 v32, v2
	v_mov_b32_e32 v33, v2
	v_mov_b32_e32 v34, v2
	v_mov_b32_e32 v35, v2
	v_mov_b32_e32 v36, v2
	v_mov_b32_e32 v37, v2
	v_mov_b32_e32 v38, v2
	v_mov_b32_e32 v39, v2
	v_mov_b32_e32 v40, v2
	v_mov_b32_e32 v41, v2
	v_mov_b32_e32 v42, v2
	v_mov_b32_e32 v43, v2
	v_mov_b32_e32 v44, v2
	v_mov_b32_e32 v45, v2
	v_mov_b32_e32 v46, v2
	v_mov_b32_e32 v47, v2
	v_mov_b32_e32 v48, v2
	v_mov_b32_e32 v49, v2
	v_mov_b32_e32 v50, v2
	v_mov_b32_e32 v51, v2
	v_mov_b32_e32 v52, v2
	v_mov_b32_e32 v53, v2
	v_mov_b32_e32 v54, v2
	v_mov_b32_e32 v55, v2
	v_mov_b32_e32 v56, v2
	v_mov_b32_e32 v57, v2
	v_mov_b32_e32 v58, v2
	v_mov_b32_e32 v59, v2
	v_mov_b32_e32 v60, v2
	v_mov_b32_e32 v61, v2
	v_mov_b32_e32 v62, v2
	v_mov_b32_e32 v63, v2
	v_mov_b32_e32 v64, v2
	v_mov_b32_e32 v65, v2
	v_readlane_b32 s9, v255, 6
	v_readlane_b32 s10, v255, 7
	v_readlane_b32 s11, v255, 8
	v_readlane_b32 s14, v255, 11
	v_readlane_b32 s15, v255, 12
	.p2align	6

; DI int get_tid() { int t = threadIdx.x; asm volatile("" : "+v"(t)); return t; }
; DI float zero_f() { float z = 0.f; asm volatile("" : "+v"(z)); return z; }
; template <int BM, class Epi>
; DI void gemm_dma(const u16* __restrict__ X, long ldx, const u16* __restrict__ W, long ldw, int K, char* smem,
;                  int m0, int n0, const Epi& epi) {
;     ...
;   const int tid = get_tid(), lane = tid & 63, wave = tid >> 6;
;   const int lr = lane & 15, g = lane >> 4;
;   const int rd = lr * 64 + ((g ^ ((4 - (lr >> 2)) & 3)) << 4);
;   const int xrow0 = BIG ? wave * 64 : (wave & 1) * (BM / 2);
;   const int wrow0 = BIG ? 0 : (wave >> 1) * 64;
;   f32x4 acc[NT][MT];
;   { const float z = zero_f();
; #pragma unroll
;   for (int a = 0; a < NT; ++a)
; #pragma unroll
;     for (int b = 0; b < MT; ++b) acc[a][b] = (f32x4){z, z, z, z}; }
;   const int wu = __builtin_amdgcn_readfirstlane(wave);
;   const unsigned sbase = (unsigned)__builtin_amdgcn_readfirstlane((int)(unsigned)(size_t)smem);
;   const int r16 = lane >> 2, chunk = (lane & 3) ^ ((4 - (r16 >> 2)) & 3);
;   const u16* xs = X + (long)(wu * XD * 16 + r16) * ldx + (chunk << 3);
;   const u16* ws = W + (long)(wu * 32 + r16) * ldw + (chunk << 3);
;   const long ldx16 = 16 * ldx, ldw16 = 16 * ldw;
;   const unsigned xdst = sbase + wu * XD * 1024, wdst = sbase + BM * 64 + wu * 2048;
;     ...
;   const int nk = K >> 5;
;   __syncthreads();
; #pragma unroll
;   for (int s = 0; s < D - 1; ++s) GD_ISSUE(s)
;   int cur = 0, nxt = D - 1, kt = 0;
.LBB0_908:
	s_and_b64 vcc, exec, s[38:39]
	s_cbranch_vccz .LBB0_903
	s_ashr_i32 s38, s6, 3
	s_ashr_i32 s39, s38, 31
	v_mov_b32_e32 v1, v185
	s_and_b32 s7, s6, 7
	s_lshl_b64 s[40:41], s[38:39], 19
	v_readlane_b32 s8, v252, 24
	v_readlane_b32 s9, v252, 25
	v_lshrrev_b32_e32 v2, 2, v1
	s_add_u32 s8, s8, s40
	v_and_b32_e32 v133, 15, v1
	v_bfe_u32 v132, v1, 4, 2
	v_sub_u32_e32 v2, 0, v2
	s_addc_u32 s9, s9, s41
	s_lshl_b32 s10, s7, 18
	v_readlane_b32 s12, v252, 26
	v_lshlrev_b32_e32 v0, 6, v133
	v_bitop3_b32 v2, v132, v2, 3 bitop3:0x78
	v_readlane_b32 s13, v252, 27
	s_add_u32 s12, s12, s10
	v_lshl_or_b32 v134, v2, 4, v0
	v_readfirstlane_b32 s14, v1
	v_lshrrev_b32_e32 v2, 4, v1
	s_addc_u32 s13, s13, 0
	s_ashr_i32 s15, s14, 6
	v_bfe_u32 v6, v1, 2, 4
	v_sub_u32_e32 v14, 0, v2
	s_andn2_b32 s14, s14, 63
	v_xor_b32_e32 v7, v1, v14
	v_or_b32_e32 v2, s14, v6
	v_ashrrev_i32_e32 v3, 31, v2
	v_lshlrev_b32_e32 v7, 4, v7
	v_lshl_or_b32 v6, s15, 5, v6
	v_lshlrev_b64 v[2:3], 11, v[2:3]
	v_and_b32_e32 v182, 48, v7
	v_ashrrev_i32_e32 v7, 31, v6
	v_mov_b32_e32 v0, v183
	v_lshl_add_u64 v[4:5], s[8:9], 0, v[2:3]
	v_lshlrev_b64 v[6:7], 11, v[6:7]
	v_lshl_add_u64 v[4:5], v[4:5], 0, v[182:183]
	v_lshl_add_u64 v[8:9], s[12:13], 0, v[6:7]
	s_lshl_b32 s8, s15, 12
	s_barrier
	s_mov_b32 m0, s8
	s_nop 0
	global_load_lds_dwordx4 v[4:5], off
	s_mov_b64 s[16:17], 0x8000
	v_lshl_add_u64 v[10:11], v[4:5], 0, s[16:17]
	s_or_b32 s13, s8, 0x400
	s_mov_b32 m0, s13
	s_nop 0
	global_load_lds_dwordx4 v[10:11], off
	s_mov_b64 s[18:19], 0x10000
	v_lshl_add_u64 v[10:11], v[4:5], 0, s[18:19]
	s_or_b32 s13, s8, 0x800
	s_mov_b32 m0, s13
	s_nop 0
	global_load_lds_dwordx4 v[10:11], off
	s_mov_b64 s[20:21], 0x18000
	s_lshl_b32 s12, s15, 11
	v_lshl_add_u64 v[10:11], v[4:5], 0, s[20:21]
	s_or_b32 s13, s8, 0xc00
	s_mov_b32 m0, s13
	s_nop 0
	global_load_lds_dwordx4 v[10:11], off
	v_lshl_add_u64 v[8:9], v[8:9], 0, v[182:183]
	s_add_i32 s9, s12, 0x4000
	s_mov_b32 m0, s9
	s_nop 0
	global_load_lds_dwordx4 v[8:9], off
	v_lshl_add_u64 v[10:11], v[8:9], 0, s[16:17]
	s_add_i32 s13, s12, 0x4400
	s_mov_b32 m0, s13
	s_nop 0
	global_load_lds_dwordx4 v[10:11], off
	v_lshl_add_u64 v[10:11], v[4:5], 0, 64
	s_add_i32 s13, s8, 0x6000
	s_mov_b32 m0, s13
	s_nop 0
	global_load_lds_dwordx4 v[10:11], off
	s_mov_b64 s[22:23], 0x8040
	v_lshl_add_u64 v[10:11], v[4:5], 0, s[22:23]
	s_add_i32 s13, s8, 0x6400
	s_mov_b32 m0, s13
	s_nop 0
	global_load_lds_dwordx4 v[10:11], off
	s_mov_b64 s[14:15], 0x10040
	v_lshl_add_u64 v[10:11], v[4:5], 0, s[14:15]
	s_add_i32 s13, s8, 0x6800
	s_mov_b32 m0, s13
	s_nop 0
	global_load_lds_dwordx4 v[10:11], off
	s_mov_b64 s[14:15], 0x18040
	v_lshl_add_u64 v[4:5], v[4:5], 0, s[14:15]
	s_add_i32 s13, s8, 0x6c00
	s_mov_b32 m0, s13
	s_nop 0
	global_load_lds_dwordx4 v[4:5], off
	v_lshl_add_u64 v[12:13], v[8:9], 0, 64
	s_add_i32 s13, s12, 0xa000
	s_mov_b32 m0, s13
	s_nop 0
	global_load_lds_dwordx4 v[12:13], off
	v_lshl_add_u64 v[4:5], v[8:9], 0, s[22:23]
	s_add_i32 s12, s12, 0xa400
	s_mov_b32 m0, s12
	s_nop 0
	global_load_lds_dwordx4 v[4:5], off
	v_and_b32_e32 v135, 0xffffffc0, v1
	v_bitop3_b32 v1, v1, 3, v14 bitop3:0x48
	v_lshl_add_u64 v[4:5], s[34:35], 0, v[6:7]
	v_lshlrev_b32_e32 v182, 4, v1
	v_readlane_b32 s12, v254, 59
	v_lshl_add_u64 v[4:5], v[4:5], 0, v[182:183]
	v_readlane_b32 s13, v254, 60
	v_lshl_add_u64 v[2:3], s[40:41], 0, v[2:3]
	v_or_b32_e32 v2, v2, v182
	v_lshl_add_u64 v[128:129], s[12:13], 0, v[4:5]
	v_readlane_b32 s12, v254, 61
	v_readlane_b32 s13, v254, 62
	s_mov_b32 s10, 2
	s_mov_b32 s11, 0
	v_lshlrev_b32_e32 v136, 6, v135
	v_lshl_add_u64 v[130:131], s[12:13], 0, v[2:3]
	s_mov_b64 s[40:41], 0
	v_mov_b32_e32 v1, v0
	v_mov_b32_e32 v2, v0
	v_mov_b32_e32 v3, v0
	v_mov_b32_e32 v4, v0
	v_mov_b32_e32 v5, v0
	v_mov_b32_e32 v6, v0
	v_mov_b32_e32 v7, v0
	v_mov_b32_e32 v8, v0
	v_mov_b32_e32 v9, v0
	v_mov_b32_e32 v10, v0
	v_mov_b32_e32 v11, v0
	v_mov_b32_e32 v12, v0
	v_mov_b32_e32 v13, v0
	v_mov_b32_e32 v14, v0
	v_mov_b32_e32 v15, v0
	v_mov_b32_e32 v16, v0
	v_mov_b32_e32 v17, v0
	v_mov_b32_e32 v18, v0
	v_mov_b32_e32 v19, v0
	v_mov_b32_e32 v20, v0
	v_mov_b32_e32 v21, v0
	v_mov_b32_e32 v22, v0
	v_mov_b32_e32 v23, v0
	v_mov_b32_e32 v24, v0
	v_mov_b32_e32 v25, v0
	v_mov_b32_e32 v26, v0
	v_mov_b32_e32 v27, v0
	v_mov_b32_e32 v28, v0
	v_mov_b32_e32 v29, v0
	v_mov_b32_e32 v30, v0
	v_mov_b32_e32 v31, v0
	v_mov_b32_e32 v32, v0
	v_mov_b32_e32 v33, v0
	v_mov_b32_e32 v34, v0
	v_mov_b32_e32 v35, v0
	v_mov_b32_e32 v36, v0
	v_mov_b32_e32 v37, v0
	v_mov_b32_e32 v38, v0
	v_mov_b32_e32 v39, v0
	v_mov_b32_e32 v40, v0
	v_mov_b32_e32 v41, v0
	v_mov_b32_e32 v42, v0
	v_mov_b32_e32 v43, v0
	v_mov_b32_e32 v44, v0
	v_mov_b32_e32 v45, v0
	v_mov_b32_e32 v46, v0
	v_mov_b32_e32 v47, v0
	v_mov_b32_e32 v48, v0
	v_mov_b32_e32 v49, v0
	v_mov_b32_e32 v50, v0
	v_mov_b32_e32 v51, v0
	v_mov_b32_e32 v52, v0
	v_mov_b32_e32 v53, v0
	v_mov_b32_e32 v54, v0
	v_mov_b32_e32 v55, v0
	v_mov_b32_e32 v56, v0
	v_mov_b32_e32 v57, v0
	v_mov_b32_e32 v58, v0
	v_mov_b32_e32 v59, v0
	v_mov_b32_e32 v60, v0
	v_mov_b32_e32 v61, v0
	v_mov_b32_e32 v62, v0
	v_mov_b32_e32 v63, v0
	v_mov_b32_e32 v64, v0
	v_mov_b32_e32 v65, v0
	v_mov_b32_e32 v66, v0
	v_mov_b32_e32 v67, v0
	v_mov_b32_e32 v68, v0
	v_mov_b32_e32 v69, v0
	v_mov_b32_e32 v70, v0
	v_mov_b32_e32 v71, v0
	v_mov_b32_e32 v72, v0
	v_mov_b32_e32 v73, v0
	v_mov_b32_e32 v74, v0
	v_mov_b32_e32 v75, v0
	v_mov_b32_e32 v76, v0
	v_mov_b32_e32 v77, v0
	v_mov_b32_e32 v78, v0
	v_mov_b32_e32 v79, v0
	v_mov_b32_e32 v80, v0
	v_mov_b32_e32 v81, v0
	v_mov_b32_e32 v82, v0
	v_mov_b32_e32 v83, v0
	v_mov_b32_e32 v84, v0
	v_mov_b32_e32 v85, v0
	v_mov_b32_e32 v86, v0
	v_mov_b32_e32 v87, v0
	v_mov_b32_e32 v88, v0
	v_mov_b32_e32 v89, v0
	v_mov_b32_e32 v90, v0
	v_mov_b32_e32 v91, v0
	v_mov_b32_e32 v92, v0
	v_mov_b32_e32 v93, v0
	v_mov_b32_e32 v94, v0
	v_mov_b32_e32 v95, v0
	v_mov_b32_e32 v96, v0
	v_mov_b32_e32 v97, v0
	v_mov_b32_e32 v98, v0
	v_mov_b32_e32 v99, v0
	v_mov_b32_e32 v100, v0
	v_mov_b32_e32 v101, v0
	v_mov_b32_e32 v102, v0
	v_mov_b32_e32 v103, v0
	v_mov_b32_e32 v104, v0
	v_mov_b32_e32 v105, v0
	v_mov_b32_e32 v106, v0
	v_mov_b32_e32 v107, v0
	v_mov_b32_e32 v108, v0
	v_mov_b32_e32 v109, v0
	v_mov_b32_e32 v110, v0
	v_mov_b32_e32 v111, v0
	v_mov_b32_e32 v112, v0
	v_mov_b32_e32 v113, v0
	v_mov_b32_e32 v114, v0
	v_mov_b32_e32 v115, v0
	v_mov_b32_e32 v116, v0
	v_mov_b32_e32 v117, v0
	v_mov_b32_e32 v118, v0
	v_mov_b32_e32 v119, v0
	v_mov_b32_e32 v120, v0
	v_mov_b32_e32 v121, v0
	v_mov_b32_e32 v122, v0
	v_mov_b32_e32 v123, v0
	v_mov_b32_e32 v124, v0
	v_mov_b32_e32 v125, v0
	v_mov_b32_e32 v126, v0
	v_mov_b32_e32 v127, v0
	.p2align	6

; DI int get_tid() { int t = threadIdx.x; asm volatile("" : "+v"(t)); return t; }
; DI int get_bid() { int b = blockIdx.x; asm volatile("" : "+s"(b)); return b; }
; DI float zero_f() { float z = 0.f; asm volatile("" : "+v"(z)); return z; }
; DI void attn_phase(const Params& p, char* smem, bool dry) {
;     ...
;   __syncthreads();
;   if (get_tid() == 0) { const unsigned zu = __float_as_uint(zero_f()); *(uint4*)(smem + 81904) = make_uint4(zu, zu, zu, zu); }
; DI void phase_odd(const Params& p, int o, int sub, char* smem) {
;     ...
;     for (int t = get_bid(); t < 512 + 64; t += gridDim.x) {
;       if (t < 512) {
;         const int tm = t >> 3, tn = t & 7;
;         gemm_dma<256>(ao + (size_t)tm * 256 * 1024, 1024, W + WO_O + (size_t)tn * 128 * 1024, 1024, 1024, smem, tm * 256, tn * 128, epi);
.LBB0_960:
	s_mov_b64 s[40:41], exec
	v_readlane_b32 s4, v255, 30
	v_readlane_b32 s5, v255, 31
	s_and_b64 s[4:5], s[40:41], s[4:5]
	s_mov_b64 exec, s[4:5]
	v_mov_b32_e32 v1, v0
	v_mov_b32_e32 v2, v0
	v_mov_b32_e32 v3, v0
	ds_write_b128 v201, v[0:3]
	s_or_b64 exec, exec, s[40:41]
	s_andn2_b64 vcc, exec, s[38:39]
	s_cbranch_vccnz .LBB0_974
	s_mov_b32 s4, s2
	s_waitcnt vmcnt(0)
	s_branch .LBB0_966
	.p2align	6

; DI int get_tid() { int t = threadIdx.x; asm volatile("" : "+v"(t)); return t; }
; DI float zero_f() { float z = 0.f; asm volatile("" : "+v"(z)); return z; }
; template <int MT, class Epi>
; DI void gemm_tile(const u16* __restrict__ X, long ldx, const u16* __restrict__ W, long ldw, int K, char* smem,
;                   int m0, int n0, const Epi& epi, bool pre = false, const u16* Xn = nullptr, const u16* Wn = nullptr) {
;   const int tid = get_tid(), lane = tid & 63, wave = tid >> 6;
;   const int wm = wave & 1, wn = wave >> 1;
;   const int lr = lane & 15, g = lane >> 4;
;   const int rsw = (lr >> 1) & 7;
;   f32x4 acc[4][MT];
;   { const float z = zero_f();
; #pragma unroll
;   for (int a = 0; a < 4; ++a)
; #pragma unroll
;     for (int b = 0; b < MT; ++b) acc[a][b] = (f32x4){z, z, z, z}; }
;   const int wu = __builtin_amdgcn_readfirstlane(wave);
;   const unsigned sbase = (unsigned)__builtin_amdgcn_readfirstlane((int)(unsigned)(size_t)smem);
;   const int r8 = lane >> 3, c0 = (lane & 7) ^ (r8 >> 1);
;   const long oxe = (long)(wu * MT * 8 + r8) * ldx + (c0 << 3), oxo = (long)(wu * MT * 8 + r8) * ldx + ((c0 ^ 4) << 3);
;   const long owe = (long)(wu * 32 + r8) * ldw + (c0 << 3), owo = (long)(wu * 32 + r8) * ldw + ((c0 ^ 4) << 3);
;   const u16 *xe = X + oxe, *xo = X + oxo, *we = W + owe, *wo = W + owo;
;   const long ldx8 = 8 * ldx, ldw8 = 8 * ldw;
;   const unsigned xdst = sbase + wu * MT * 1024, wdst = sbase + 16384 + wu * 4096;
;     ...
;   if (!pre) {
;     __syncthreads();
;     GT_DMA(0u)
;   } else {
;     xe += 64; xo += 64; we += 64; wo += 64;
;   }
;   const int nk = K >> 6;
;   int kt = 0;
.LBB0_1025:
	v_and_b32_e32 v77, 1, v4
	v_and_b32_e32 v78, 15, v3
	v_lshrrev_b32_e32 v4, 1, v3
	v_ashrrev_i32_e32 v79, 7, v3
	v_bfe_u32 v3, v3, 1, 3
	v_bitop3_b32 v3, v76, v3, 4 bitop3:0x36
	v_add_u32_e32 v2, s7, v2
	v_lshlrev_b32_e32 v82, 4, v3
	v_ashrrev_i32_e32 v3, 31, v2
	v_xor_b32_e32 v6, 32, v5
	v_bitop3_b32 v4, v76, v4, 7 bitop3:0x78
	v_lshlrev_b64 v[2:3], 11, v[2:3]
	v_lshlrev_b32_e32 v84, 4, v4
	v_lshl_add_u64 v[4:5], s[44:45], 0, v[2:3]
	v_lshlrev_b32_e32 v182, 1, v6
	v_readlane_b32 s8, v255, 5
	v_lshl_add_u64 v[6:7], v[4:5], 0, v[182:183]
	v_readlane_b32 s12, v255, 9
	v_readlane_b32 s13, v255, 10
	v_lshl_add_u64 v[2:3], s[40:41], 0, v[2:3]
	v_lshlrev_b32_e32 v80, 13, v77
	v_lshl_add_u64 v[68:69], s[12:13], 0, v[6:7]
	v_lshlrev_b32_e32 v6, 4, v1
	v_mov_b32_e32 v7, v183
	v_lshl_add_u64 v[4:5], v[4:5], 0, v[6:7]
	v_lshl_add_u64 v[70:71], s[12:13], 0, v[4:5]
	v_lshl_add_u64 v[4:5], v[2:3], 0, v[182:183]
	v_lshl_add_u64 v[2:3], v[2:3], 0, v[6:7]
	v_lshlrev_b32_e32 v81, 7, v78
	v_lshlrev_b32_e32 v83, 13, v79
	v_lshl_add_u64 v[72:73], s[0:1], 0, v[4:5]
	v_lshl_add_u64 v[74:75], s[12:13], 0, v[2:3]
	s_mov_b64 s[40:41], 0
	s_mov_b32 s8, 0
	v_mov_b32_e32 v1, v0
	v_mov_b32_e32 v2, v0
	v_mov_b32_e32 v3, v0
	v_mov_b32_e32 v4, v0
	v_mov_b32_e32 v5, v0
	v_mov_b32_e32 v6, v0
	v_mov_b32_e32 v7, v0
	v_mov_b32_e32 v8, v0
	v_mov_b32_e32 v9, v0
	v_mov_b32_e32 v10, v0
	v_mov_b32_e32 v11, v0
	v_mov_b32_e32 v12, v0
	v_mov_b32_e32 v13, v0
	v_mov_b32_e32 v14, v0
	v_mov_b32_e32 v15, v0
	v_mov_b32_e32 v16, v0
	v_mov_b32_e32 v17, v0
	v_mov_b32_e32 v18, v0
	v_mov_b32_e32 v19, v0
	v_mov_b32_e32 v20, v0
	v_mov_b32_e32 v21, v0
	v_mov_b32_e32 v22, v0
	v_mov_b32_e32 v23, v0
	v_mov_b32_e32 v24, v0
	v_mov_b32_e32 v25, v0
	v_mov_b32_e32 v26, v0
	v_mov_b32_e32 v27, v0
	v_mov_b32_e32 v28, v0
	v_mov_b32_e32 v29, v0
	v_mov_b32_e32 v30, v0
	v_mov_b32_e32 v31, v0
	v_mov_b32_e32 v32, v0
	v_mov_b32_e32 v33, v0
	v_mov_b32_e32 v34, v0
	v_mov_b32_e32 v35, v0
	v_mov_b32_e32 v36, v0
	v_mov_b32_e32 v37, v0
	v_mov_b32_e32 v38, v0
	v_mov_b32_e32 v39, v0
	v_mov_b32_e32 v40, v0
	v_mov_b32_e32 v41, v0
	v_mov_b32_e32 v42, v0
	v_mov_b32_e32 v43, v0
	v_mov_b32_e32 v44, v0
	v_mov_b32_e32 v45, v0
	v_mov_b32_e32 v46, v0
	v_mov_b32_e32 v47, v0
	v_mov_b32_e32 v48, v0
	v_mov_b32_e32 v49, v0
	v_mov_b32_e32 v50, v0
	v_mov_b32_e32 v51, v0
	v_mov_b32_e32 v52, v0
	v_mov_b32_e32 v53, v0
	v_mov_b32_e32 v54, v0
	v_mov_b32_e32 v55, v0
	v_mov_b32_e32 v56, v0
	v_mov_b32_e32 v57, v0
	v_mov_b32_e32 v58, v0
	v_mov_b32_e32 v59, v0
	v_mov_b32_e32 v60, v0
	v_mov_b32_e32 v61, v0
	v_mov_b32_e32 v62, v0
	v_mov_b32_e32 v63, v0
	v_readlane_b32 s9, v255, 6
	v_readlane_b32 s10, v255, 7
	v_readlane_b32 s11, v255, 8
	v_readlane_b32 s14, v255, 11
	v_readlane_b32 s15, v255, 12
	.p2align	6

; DI int get_tid() { int t = threadIdx.x; asm volatile("" : "+v"(t)); return t; }
; DI float zero_f() { float z = 0.f; asm volatile("" : "+v"(z)); return z; }
; template <int BM, class Epi>
; DI void gemm_dma(const u16* __restrict__ X, long ldx, const u16* __restrict__ W, long ldw, int K, char* smem,
;                  int m0, int n0, const Epi& epi) {
;     ...
;   const int tid = get_tid(), lane = tid & 63, wave = tid >> 6;
;   const int lr = lane & 15, g = lane >> 4;
;   const int rd = lr * 64 + ((g ^ ((4 - (lr >> 2)) & 3)) << 4);
;   const int xrow0 = BIG ? wave * 64 : (wave & 1) * (BM / 2);
;   const int wrow0 = BIG ? 0 : (wave >> 1) * 64;
;   f32x4 acc[NT][MT];
;   { const float z = zero_f();
; #pragma unroll
;   for (int a = 0; a < NT; ++a)
; #pragma unroll
;     for (int b = 0; b < MT; ++b) acc[a][b] = (f32x4){z, z, z, z}; }
;   const int wu = __builtin_amdgcn_readfirstlane(wave);
;   const unsigned sbase = (unsigned)__builtin_amdgcn_readfirstlane((int)(unsigned)(size_t)smem);
;   const int r16 = lane >> 2, chunk = (lane & 3) ^ ((4 - (r16 >> 2)) & 3);
;   const u16* xs = X + (long)(wu * XD * 16 + r16) * ldx + (chunk << 3);
;   const u16* ws = W + (long)(wu * 32 + r16) * ldw + (chunk << 3);
;   const long ldx16 = 16 * ldx, ldw16 = 16 * ldw;
;   const unsigned xdst = sbase + wu * XD * 1024, wdst = sbase + BM * 64 + wu * 2048;
;     ...
;   const int nk = K >> 5;
;   __syncthreads();
; #pragma unroll
;   for (int s = 0; s < D - 1; ++s) GD_ISSUE(s)
;   int cur = 0, nxt = D - 1, kt = 0;
; DI void phase_even(const Params& p, int e, int sub, char* smem) {
;     ...
;         const int tm = t >> 3, tn = t & 7;
;         gemm_dma<256>(gbuf + (size_t)tm * 256 * 2048, 2048, W + WE_OUT + (size_t)tn * 128 * 2048, 2048, 2048, smem, tm * 256, tn * 128, epi);
.LBB0_1137:
	s_and_b64 vcc, exec, s[40:41]
	s_cbranch_vccz .LBB0_1132
	s_ashr_i32 s40, s6, 3
	s_ashr_i32 s41, s40, 31
	v_mov_b32_e32 v1, v185
	s_and_b32 s7, s6, 7
	s_lshl_b64 s[42:43], s[40:41], 20
	v_readlane_b32 s8, v252, 35
	v_readlane_b32 s9, v252, 36
	v_lshrrev_b32_e32 v2, 2, v1
	s_add_u32 s8, s8, s42
	v_and_b32_e32 v133, 15, v1
	v_bfe_u32 v132, v1, 4, 2
	v_sub_u32_e32 v2, 0, v2
	s_addc_u32 s9, s9, s43
	s_lshl_b32 s10, s7, 19
	v_readlane_b32 s12, v252, 39
	v_lshlrev_b32_e32 v0, 6, v133
	v_bitop3_b32 v2, v132, v2, 3 bitop3:0x78
	v_readlane_b32 s13, v252, 40
	s_add_u32 s12, s12, s10
	v_lshl_or_b32 v134, v2, 4, v0
	v_readfirstlane_b32 s14, v1
	v_lshrrev_b32_e32 v2, 4, v1
	s_addc_u32 s13, s13, 0
	s_ashr_i32 s15, s14, 6
	v_bfe_u32 v6, v1, 2, 4
	v_sub_u32_e32 v14, 0, v2
	s_andn2_b32 s14, s14, 63
	v_xor_b32_e32 v7, v1, v14
	v_or_b32_e32 v2, s14, v6
	v_ashrrev_i32_e32 v3, 31, v2
	v_lshlrev_b32_e32 v7, 4, v7
	v_lshl_or_b32 v6, s15, 5, v6
	v_lshlrev_b64 v[2:3], 12, v[2:3]
	v_and_b32_e32 v182, 48, v7
	v_ashrrev_i32_e32 v7, 31, v6
	v_mov_b32_e32 v0, v183
	v_lshl_add_u64 v[4:5], s[8:9], 0, v[2:3]
	v_lshlrev_b64 v[6:7], 12, v[6:7]
	v_lshl_add_u64 v[4:5], v[4:5], 0, v[182:183]
	v_lshl_add_u64 v[8:9], s[12:13], 0, v[6:7]
	s_lshl_b32 s8, s15, 12
	s_waitcnt lgkmcnt(0)
	s_barrier
	s_mov_b32 m0, s8
	s_nop 0
	global_load_lds_dwordx4 v[4:5], off
	v_lshl_add_u64 v[10:11], v[4:5], 0, s[58:59]
	s_or_b32 s13, s8, 0x400
	s_mov_b32 m0, s13
	s_nop 0
	global_load_lds_dwordx4 v[10:11], off
	s_mov_b64 s[16:17], 0x20000
	v_lshl_add_u64 v[10:11], v[4:5], 0, s[16:17]
	s_or_b32 s13, s8, 0x800
	s_mov_b32 m0, s13
	s_nop 0
	global_load_lds_dwordx4 v[10:11], off
	s_mov_b64 s[18:19], 0x30000
	s_lshl_b32 s12, s15, 11
	v_lshl_add_u64 v[10:11], v[4:5], 0, s[18:19]
	s_or_b32 s13, s8, 0xc00
	s_mov_b32 m0, s13
	s_nop 0
	global_load_lds_dwordx4 v[10:11], off
	v_lshl_add_u64 v[8:9], v[8:9], 0, v[182:183]
	s_add_i32 s9, s12, 0x4000
	s_mov_b32 m0, s9
	s_nop 0
	global_load_lds_dwordx4 v[8:9], off
	v_lshl_add_u64 v[10:11], v[8:9], 0, s[58:59]
	s_add_i32 s13, s12, 0x4400
	s_mov_b32 m0, s13
	s_nop 0
	global_load_lds_dwordx4 v[10:11], off
	v_lshl_add_u64 v[10:11], v[4:5], 0, 64
	s_add_i32 s13, s8, 0x6000
	s_mov_b32 m0, s13
	s_nop 0
	global_load_lds_dwordx4 v[10:11], off
	v_lshl_add_u64 v[10:11], v[4:5], 0, s[62:63]
	s_add_i32 s13, s8, 0x6400
	s_mov_b32 m0, s13
	s_nop 0
	global_load_lds_dwordx4 v[10:11], off
	s_mov_b64 s[14:15], 0x20040
	v_lshl_add_u64 v[10:11], v[4:5], 0, s[14:15]
	s_add_i32 s13, s8, 0x6800
	s_mov_b32 m0, s13
	s_nop 0
	global_load_lds_dwordx4 v[10:11], off
	s_mov_b64 s[14:15], 0x30040
	v_lshl_add_u64 v[4:5], v[4:5], 0, s[14:15]
	s_add_i32 s13, s8, 0x6c00
	s_mov_b32 m0, s13
	s_nop 0
	global_load_lds_dwordx4 v[4:5], off
	v_lshl_add_u64 v[12:13], v[8:9], 0, 64
	s_add_i32 s13, s12, 0xa000
	s_mov_b32 m0, s13
	s_nop 0
	global_load_lds_dwordx4 v[12:13], off
	v_lshl_add_u64 v[4:5], v[8:9], 0, s[62:63]
	v_and_b32_e32 v135, 0xffffffc0, v1
	v_bitop3_b32 v1, v1, 3, v14 bitop3:0x48
	s_add_i32 s12, s12, 0xa400
	s_mov_b32 m0, s12
	s_nop 0
	global_load_lds_dwordx4 v[4:5], off
	v_lshl_add_u64 v[4:5], s[34:35], 0, v[6:7]
	v_lshlrev_b32_e32 v182, 4, v1
	v_lshl_add_u64 v[2:3], s[42:43], 0, v[2:3]
	v_lshl_add_u64 v[4:5], v[4:5], 0, v[182:183]
	v_or_b32_e32 v2, v2, v182
	s_mov_b32 s10, 2
	s_mov_b32 s11, 0
	v_lshlrev_b32_e32 v136, 6, v135
	v_lshl_add_u64 v[128:129], s[50:51], 0, v[4:5]
	v_lshl_add_u64 v[130:131], s[52:53], 0, v[2:3]
	s_mov_b64 s[42:43], 0
	v_mov_b32_e32 v1, v0
	v_mov_b32_e32 v2, v0
	v_mov_b32_e32 v3, v0
	v_mov_b32_e32 v4, v0
	v_mov_b32_e32 v5, v0
	v_mov_b32_e32 v6, v0
	v_mov_b32_e32 v7, v0
	v_mov_b32_e32 v8, v0
	v_mov_b32_e32 v9, v0
	v_mov_b32_e32 v10, v0
	v_mov_b32_e32 v11, v0
	v_mov_b32_e32 v12, v0
	v_mov_b32_e32 v13, v0
	v_mov_b32_e32 v14, v0
	v_mov_b32_e32 v15, v0
	v_mov_b32_e32 v16, v0
	v_mov_b32_e32 v17, v0
	v_mov_b32_e32 v18, v0
	v_mov_b32_e32 v19, v0
	v_mov_b32_e32 v20, v0
	v_mov_b32_e32 v21, v0
	v_mov_b32_e32 v22, v0
	v_mov_b32_e32 v23, v0
	v_mov_b32_e32 v24, v0
	v_mov_b32_e32 v25, v0
	v_mov_b32_e32 v26, v0
	v_mov_b32_e32 v27, v0
	v_mov_b32_e32 v28, v0
	v_mov_b32_e32 v29, v0
	v_mov_b32_e32 v30, v0
	v_mov_b32_e32 v31, v0
	v_mov_b32_e32 v32, v0
	v_mov_b32_e32 v33, v0
	v_mov_b32_e32 v34, v0
	v_mov_b32_e32 v35, v0
	v_mov_b32_e32 v36, v0
	v_mov_b32_e32 v37, v0
	v_mov_b32_e32 v38, v0
	v_mov_b32_e32 v39, v0
	v_mov_b32_e32 v40, v0
	v_mov_b32_e32 v41, v0
	v_mov_b32_e32 v42, v0
	v_mov_b32_e32 v43, v0
	v_mov_b32_e32 v44, v0
	v_mov_b32_e32 v45, v0
	v_mov_b32_e32 v46, v0
	v_mov_b32_e32 v47, v0
	v_mov_b32_e32 v48, v0
	v_mov_b32_e32 v49, v0
	v_mov_b32_e32 v50, v0
	v_mov_b32_e32 v51, v0
	v_mov_b32_e32 v52, v0
	v_mov_b32_e32 v53, v0
	v_mov_b32_e32 v54, v0
	v_mov_b32_e32 v55, v0
	v_mov_b32_e32 v56, v0
	v_mov_b32_e32 v57, v0
	v_mov_b32_e32 v58, v0
	v_mov_b32_e32 v59, v0
	v_mov_b32_e32 v60, v0
	v_mov_b32_e32 v61, v0
	v_mov_b32_e32 v62, v0
	v_mov_b32_e32 v63, v0
	v_mov_b32_e32 v64, v0
	v_mov_b32_e32 v65, v0
	v_mov_b32_e32 v66, v0
	v_mov_b32_e32 v67, v0
	v_mov_b32_e32 v68, v0
	v_mov_b32_e32 v69, v0
	v_mov_b32_e32 v70, v0
	v_mov_b32_e32 v71, v0
	v_mov_b32_e32 v72, v0
	v_mov_b32_e32 v73, v0
	v_mov_b32_e32 v74, v0
	v_mov_b32_e32 v75, v0
	v_mov_b32_e32 v76, v0
	v_mov_b32_e32 v77, v0
	v_mov_b32_e32 v78, v0
	v_mov_b32_e32 v79, v0
	v_mov_b32_e32 v80, v0
	v_mov_b32_e32 v81, v0
	v_mov_b32_e32 v82, v0
	v_mov_b32_e32 v83, v0
	v_mov_b32_e32 v84, v0
	v_mov_b32_e32 v85, v0
	v_mov_b32_e32 v86, v0
	v_mov_b32_e32 v87, v0
	v_mov_b32_e32 v88, v0
	v_mov_b32_e32 v89, v0
	v_mov_b32_e32 v90, v0
	v_mov_b32_e32 v91, v0
	v_mov_b32_e32 v92, v0
	v_mov_b32_e32 v93, v0
	v_mov_b32_e32 v94, v0
	v_mov_b32_e32 v95, v0
	v_mov_b32_e32 v96, v0
	v_mov_b32_e32 v97, v0
	v_mov_b32_e32 v98, v0
	v_mov_b32_e32 v99, v0
	v_mov_b32_e32 v100, v0
	v_mov_b32_e32 v101, v0
	v_mov_b32_e32 v102, v0
	v_mov_b32_e32 v103, v0
	v_mov_b32_e32 v104, v0
	v_mov_b32_e32 v105, v0
	v_mov_b32_e32 v106, v0
	v_mov_b32_e32 v107, v0
	v_mov_b32_e32 v108, v0
	v_mov_b32_e32 v109, v0
	v_mov_b32_e32 v110, v0
	v_mov_b32_e32 v111, v0
	v_mov_b32_e32 v112, v0
	v_mov_b32_e32 v113, v0
	v_mov_b32_e32 v114, v0
	v_mov_b32_e32 v115, v0
	v_mov_b32_e32 v116, v0
	v_mov_b32_e32 v117, v0
	v_mov_b32_e32 v118, v0
	v_mov_b32_e32 v119, v0
	v_mov_b32_e32 v120, v0
	v_mov_b32_e32 v121, v0
	v_mov_b32_e32 v122, v0
	v_mov_b32_e32 v123, v0
	v_mov_b32_e32 v124, v0
	v_mov_b32_e32 v125, v0
	v_mov_b32_e32 v126, v0
	v_mov_b32_e32 v127, v0
	.p2align	6
